# attention loop: SALU base adds fill the cvt-to-swap hazard slot, removed padding nops, half-B row-max written directly to v9 (on top of v041)
# baseline (speedup 1.0000x reference)
; #define SBAR() __builtin_amdgcn_sched_barrier(0)
; #define QKT(P0, P1, KP) do { if constexpr (PRE) qkt<ND0>(P0, P1, KP, qr, r32, hi, negm); else qkt<ND0>(P0, P1, KP, qr, r32, hi); } while (0)
; DEVFI void finishSM(f32x16& p0, f32x16& p1, float alpha, float& l_reg, bf16x8& pa0, bf16x8& pa1, bf16x8& pa2, bf16x8& pa3) {
; #pragma unroll
;     for (int r = 0; r < 16; ++r) p1[r] = __builtin_amdgcn_exp2f(p1[r]);
;     float ps = 0;
; #pragma unroll
;     for (int r = 0; r < 16; ++r) ps += p0[r];
; #pragma unroll
;     for (int r = 0; r < 16; ++r) ps += p1[r];
;     { auto rr = __builtin_amdgcn_permlane32_swap(__float_as_uint(ps), __float_as_uint(ps), false, false);
;       ps = __uint_as_float(rr[0]) + __uint_as_float(rr[1]); }
;     l_reg = l_reg * alpha + ps;
;     ...
;     PK4(p0, 0, pa0); PK4(p0, 8, pa1); PK4(p1, 0, pa2); PK4(p1, 8, pa3);
;     ...
; }
; template <int DQK, int DV, bool PRE = false>
; DEVFI void attn_unit(const bf16_t* __restrict__ Qb, int ldq, const bf16_t* __restrict__ Kh, int ldk, const bf16_t* __restrict__ Vh, int ldv,
;                      bf16_t* __restrict__ Ob, int ldo, int seq, float scale, char* lds) {
;     ...
;         SBAR(); QKT(pB0, pB1, K_lds + SHM_K);
;         finishSM(pA0, pA1, alA, l_reg, pa0, pa1, pa2, pa3); SBAR();
;         SLOAD(1, (j + 2) * KVBLK); SBAR();
.LBB0_1151:
	ds_read_b128 v[0:3], v177 offset:32768
	ds_read_b128 v[4:7], v177 offset:40960
	v_add_f32_e32 v8, v203, v205
	v_add_f32_e32 v8, v189, v8
	s_waitcnt lgkmcnt(1)
	v_mfma_f32_32x32x16_bf16 v[94:109], v[0:3], v[130:133], v[46:61]
	v_add_f32_e32 v8, v204, v8
	v_add_f32_e32 v8, v187, v8
	v_add_f32_e32 v8, v202, v8
	v_add_f32_e32 v8, v186, v8
	v_add_f32_e32 v8, v188, v8
	v_add_f32_e32 v8, v183, v8
	v_add_f32_e32 v8, v185, v8
	s_waitcnt lgkmcnt(0)
	v_mfma_f32_32x32x16_bf16 v[78:93], v[4:7], v[130:133], v[46:61]
	ds_read_b128 v[0:3], v178 offset:32768
	ds_read_b128 v[4:7], v178 offset:40960
	v_add_f32_e32 v8, v163, v8
	v_add_f32_e32 v8, v184, v8
	v_add_f32_e32 v8, v161, v8
	v_add_f32_e32 v8, v182, v8
	v_add_f32_e32 v8, v160, v8
	v_add_f32_e32 v8, v162, v8
	s_waitcnt lgkmcnt(1)
	v_mfma_f32_32x32x16_bf16 v[94:109], v[0:3], v[126:129], v[94:109]
	v_exp_f32_e32 v70, v70
	v_exp_f32_e32 v71, v71
	v_exp_f32_e32 v72, v72
	v_exp_f32_e32 v73, v73
	v_exp_f32_e32 v74, v74
	v_exp_f32_e32 v75, v75
	v_exp_f32_e32 v76, v76
	s_waitcnt lgkmcnt(0)
	v_mfma_f32_32x32x16_bf16 v[78:93], v[4:7], v[126:129], v[78:93]
	ds_read_b128 v[0:3], v176 offset:32768
	ds_read_b128 v[4:7], v176 offset:40960
	v_exp_f32_e32 v77, v77
	s_waitcnt lgkmcnt(1)
	v_mfma_f32_32x32x16_bf16 v[94:109], v[0:3], v[122:125], v[94:109]
	s_waitcnt lgkmcnt(0)
	v_mfma_f32_32x32x16_bf16 v[78:93], v[4:7], v[122:125], v[78:93]
	ds_read_b128 v[0:3], v175 offset:32768
	ds_read_b128 v[4:7], v175 offset:40960
	s_waitcnt lgkmcnt(1)
	v_mfma_f32_32x32x16_bf16 v[94:109], v[0:3], v[118:121], v[94:109]
	s_waitcnt lgkmcnt(0)
	v_mfma_f32_32x32x16_bf16 v[78:93], v[4:7], v[118:121], v[78:93]
	ds_read_b128 v[0:3], v174 offset:32768
	ds_read_b128 v[4:7], v174 offset:40960
	s_waitcnt lgkmcnt(1)
	v_mfma_f32_32x32x16_bf16 v[94:109], v[0:3], v[114:117], v[94:109]
	s_waitcnt lgkmcnt(0)
	v_mfma_f32_32x32x16_bf16 v[78:93], v[4:7], v[114:117], v[78:93]
	ds_read_b128 v[0:3], v172 offset:32768
	ds_read_b128 v[4:7], v172 offset:40960
	s_waitcnt lgkmcnt(1)
	v_mfma_f32_32x32x16_bf16 v[94:109], v[0:3], v[110:113], v[94:109]
	v_exp_f32_e32 v0, v62
	v_exp_f32_e32 v1, v63
	v_exp_f32_e32 v2, v64
	v_exp_f32_e32 v3, v65
	v_add_f32_e32 v8, v0, v8
	v_add_f32_e32 v8, v1, v8
	v_add_f32_e32 v8, v2, v8
	s_waitcnt lgkmcnt(0)
	v_mfma_f32_32x32x16_bf16 v[78:93], v[4:7], v[110:113], v[78:93]
	v_exp_f32_e32 v4, v66
	v_exp_f32_e32 v5, v67
	v_exp_f32_e32 v6, v68
	v_exp_f32_e32 v7, v69
	v_add_f32_e32 v8, v3, v8
	v_add_f32_e32 v8, v4, v8
	v_add_f32_e32 v8, v5, v8
	v_add_f32_e32 v8, v6, v8
	v_add_f32_e32 v8, v7, v8
	v_add_f32_e32 v8, v70, v8
	v_add_f32_e32 v8, v71, v8
	v_add_f32_e32 v8, v72, v8
	v_add_f32_e32 v8, v73, v8
	v_add_f32_e32 v8, v74, v8
	v_add_f32_e32 v8, v75, v8
	v_add_f32_e32 v8, v76, v8
	v_add_f32_e32 v13, v77, v8
	v_cvt_pk_bf16_f32 v8, v203, v205
	v_cvt_pk_bf16_f32 v9, v189, v204
	v_cvt_pk_bf16_f32 v10, v187, v202
	v_cvt_pk_bf16_f32 v11, v186, v188
	v_cvt_pk_bf16_f32 v62, v183, v185
	v_cvt_pk_bf16_f32 v63, v163, v184
	v_cvt_pk_bf16_f32 v64, v161, v182
	v_cvt_pk_bf16_f32 v65, v160, v162
	v_cvt_pk_bf16_f32 v66, v0, v1
	v_cvt_pk_bf16_f32 v67, v2, v3
	v_cvt_pk_bf16_f32 v68, v4, v5
	v_cvt_pk_bf16_f32 v69, v6, v7
	v_cvt_pk_bf16_f32 v70, v70, v71
	v_cvt_pk_bf16_f32 v71, v72, v73
	v_cvt_pk_bf16_f32 v72, v74, v75
	v_cvt_pk_bf16_f32 v73, v76, v77
	s_add_u32 s100, s10, 0x2cc48000
	s_addc_u32 s101, s11, 0
	v_permlane32_swap_b32_e32 v8, v10
	v_permlane32_swap_b32_e32 v9, v11
	v_permlane32_swap_b32_e32 v62, v64
	v_permlane32_swap_b32_e32 v63, v65
	v_permlane32_swap_b32_e32 v66, v68
	v_permlane32_swap_b32_e32 v67, v69
	v_permlane32_swap_b32_e32 v70, v72
	v_permlane32_swap_b32_e32 v71, v73
	global_load_dwordx4 v[0:3], v158, s[100:101]
	s_and_saveexec_b64 s[0:1], s[42:43]
	s_cbranch_execz .LBB0_1153
	global_load_dwordx4 v[138:141], v154, s[100:101]
; #define SBAR() __builtin_amdgcn_sched_barrier(0)
; template <int OFF> DEVFI s16x4 tr_read(int vb) { s16x4 r; asm volatile("ds_read_b64_tr_b16 %0, %1 offset:%2" : "=&v"(r) : "v"(vb), "i"(OFF) : "memory"); return r; }
; DEVFI void partialSM2(f32x16& p0, f32x16& p1, float& mhat, f32x16& negm, float& alpha, const float thr2, const bool first) {
;     float pmax = p0[0];
; #pragma unroll
;     for (int r = 1; r < 16; ++r) pmax = fmaxf(pmax, p0[r]);
; #pragma unroll
;     for (int r = 0; r < 16; ++r) pmax = fmaxf(pmax, p1[r]);
;     { auto rr = __builtin_amdgcn_permlane32_swap(__float_as_uint(pmax), __float_as_uint(pmax), false, false);
;       pmax = fmaxf(__uint_as_float(rr[0]), __uint_as_float(rr[1])); }
;     alpha = 1.f;
;     if (first || !__all(pmax <= thr2)) {
;         const float dl = first ? pmax : fmaxf(pmax, 0.f);
;         mhat += dl; alpha = first ? 1.f : __builtin_amdgcn_exp2f(-dl);
; #pragma unroll
;         for (int r = 0; r < 16; ++r) { p0[r] -= dl; p1[r] -= dl; }
; #pragma unroll
;         for (int r = 0; r < 16; ++r) negm[r] = -mhat;
;         asm volatile("" : "+v"(negm));
; template <int NCB, int D0> DEVFI void pv_one(f32x16& od, int vb, bf16x8 pa0, bf16x8 pa1, bf16x8 pa2, bf16x8 pa3) {
;     ...
;     const s16x4 l0 = tr_read<VOFF(0, 0)>(vb), h0 = tr_read<VOFF(0, 1)>(vb), l1 = tr_read<VOFF(1, 0)>(vb), h1 = tr_read<VOFF(1, 1)>(vb);
;     const s16x4 l2 = tr_read<VOFF(2, 0)>(vb), h2 = tr_read<VOFF(2, 1)>(vb), l3 = tr_read<VOFF(3, 0)>(vb), h3 = tr_read<VOFF(3, 1)>(vb);
;     ...
;     asm volatile("s_waitcnt lgkmcnt(0)" ::: "memory"); SBAR();
;     ...
;     od = __builtin_amdgcn_mfma_f32_32x32x16_bf16(pa0, PK(l0, h0), od, 0, 0, 0);
;     od = __builtin_amdgcn_mfma_f32_32x32x16_bf16(pa1, PK(l1, h1), od, 0, 0, 0);
;     od = __builtin_amdgcn_mfma_f32_32x32x16_bf16(pa2, PK(l2, h2), od, 0, 0, 0);
;     od = __builtin_amdgcn_mfma_f32_32x32x16_bf16(pa3, PK(l3, h3), od, 0, 0, 0);
.LBB0_1153:
	s_or_b64 exec, exec, s[0:1]
	s_add_u32 s100, s10, 0x2fc30000
	s_addc_u32 s101, s11, 0
	global_load_dwordx4 v[4:7], v156, s[100:101]
	ds_read_b64_tr_b16 v[74:75], v171 offset:0
	ds_read_b64_tr_b16 v[76:77], v171 offset:0x400
	ds_read_b64_tr_b16 v[182:183], v171 offset:0x800
	ds_read_b64_tr_b16 v[184:185], v171 offset:0xc00
	ds_read_b64_tr_b16 v[186:187], v171 offset:0x1000
	ds_read_b64_tr_b16 v[188:189], v171 offset:0x1400
	ds_read_b64_tr_b16 v[202:203], v171 offset:0x1800
	ds_read_b64_tr_b16 v[204:205], v171 offset:0x1c00
	s_waitcnt lgkmcnt(6)
	s_nop 0
	v_mfma_f32_32x32x16_bf16 v[30:45], v[8:11], v[74:77], v[30:45]
	ds_read_b64_tr_b16 v[74:75], v171 offset:0x200
	ds_read_b64_tr_b16 v[76:77], v171 offset:0x600
	s_waitcnt lgkmcnt(6)
	v_mfma_f32_32x32x16_bf16 v[30:45], v[62:65], v[182:185], v[30:45]
	ds_read_b64_tr_b16 v[182:183], v171 offset:0xa00
	ds_read_b64_tr_b16 v[184:185], v171 offset:0xe00
	s_waitcnt lgkmcnt(6)
	v_mfma_f32_32x32x16_bf16 v[30:45], v[66:69], v[186:189], v[30:45]
	ds_read_b64_tr_b16 v[186:187], v171 offset:0x1200
	ds_read_b64_tr_b16 v[188:189], v171 offset:0x1600
	s_waitcnt lgkmcnt(6)
	v_mfma_f32_32x32x16_bf16 v[30:45], v[70:73], v[202:205], v[30:45]
	ds_read_b64_tr_b16 v[202:203], v171 offset:0x1a00
	ds_read_b64_tr_b16 v[204:205], v171 offset:0x1e00
	s_waitcnt lgkmcnt(6)
	v_mfma_f32_32x32x16_bf16 v[14:29], v[8:11], v[74:77], v[14:29]
	v_max_f32_e32 v8, v94, v95
	v_max3_f32 v8, v8, v96, v97
	v_max3_f32 v8, v8, v98, v99
	v_max3_f32 v8, v8, v100, v101
	v_max3_f32 v8, v8, v102, v103
	s_waitcnt lgkmcnt(4)
	v_mfma_f32_32x32x16_bf16 v[14:29], v[62:65], v[182:185], v[14:29]
	v_max3_f32 v8, v8, v104, v105
	v_max3_f32 v8, v8, v106, v107
	v_max3_f32 v8, v8, v108, v109
	v_max3_f32 v8, v8, v78, v79
	v_max3_f32 v8, v8, v80, v81
	v_max3_f32 v8, v8, v82, v83
	v_max3_f32 v8, v8, v84, v85
	s_waitcnt lgkmcnt(2)
	v_mfma_f32_32x32x16_bf16 v[14:29], v[66:69], v[186:189], v[14:29]
	v_max3_f32 v8, v8, v86, v87
	v_max3_f32 v8, v8, v88, v89
	v_max3_f32 v8, v8, v90, v91
	v_max3_f32 v8, v8, v92, v93
	s_waitcnt lgkmcnt(0)
	v_mfma_f32_32x32x16_bf16 v[14:29], v[70:73], v[202:205], v[14:29]
	v_cmp_ge_f32_e32 vcc, s33, v8
	s_cmp_eq_u64 vcc, exec
	s_cselect_b32 s100, 0, 1
	v_mov_b32_e32 v181, 1.0
	s_cbranch_scc1 .LBB0_1155
	v_mov_b32_e32 v9, v8
	s_nop 1
	v_permlane32_swap_b32_e32 v8, v9
	v_max_f32_e32 v8, v8, v9
	v_max_f32_e32 v8, v8, v8
	v_max_f32_e32 v8, 0, v8
	v_exp_f32_e64 v181, -v8
	v_add_f32_e32 v168, v168, v8
	v_xor_b32_e32 v46, 0x80000000, v168
	v_pk_add_f32 v[94:95], v[94:95], v[8:9] op_sel_hi:[1,0] neg_lo:[0,1] neg_hi:[0,1]
	v_pk_add_f32 v[96:97], v[96:97], v[8:9] op_sel_hi:[1,0] neg_lo:[0,1] neg_hi:[0,1]
	v_pk_add_f32 v[98:99], v[98:99], v[8:9] op_sel_hi:[1,0] neg_lo:[0,1] neg_hi:[0,1]
	v_pk_add_f32 v[100:101], v[100:101], v[8:9] op_sel_hi:[1,0] neg_lo:[0,1] neg_hi:[0,1]
	v_pk_add_f32 v[102:103], v[102:103], v[8:9] op_sel_hi:[1,0] neg_lo:[0,1] neg_hi:[0,1]
	v_pk_add_f32 v[104:105], v[104:105], v[8:9] op_sel_hi:[1,0] neg_lo:[0,1] neg_hi:[0,1]
	v_pk_add_f32 v[106:107], v[106:107], v[8:9] op_sel_hi:[1,0] neg_lo:[0,1] neg_hi:[0,1]
	v_pk_add_f32 v[108:109], v[108:109], v[8:9] op_sel_hi:[1,0] neg_lo:[0,1] neg_hi:[0,1]
	v_sub_f32_e32 v93, v93, v8
	v_sub_f32_e32 v92, v92, v8
	v_sub_f32_e32 v91, v91, v8
	v_sub_f32_e32 v90, v90, v8
	v_sub_f32_e32 v89, v89, v8
	v_sub_f32_e32 v88, v88, v8
	v_sub_f32_e32 v87, v87, v8
	v_sub_f32_e32 v86, v86, v8
	v_sub_f32_e32 v85, v85, v8
	v_sub_f32_e32 v84, v84, v8
	v_sub_f32_e32 v83, v83, v8
	v_sub_f32_e32 v82, v82, v8
	v_sub_f32_e32 v81, v81, v8
	v_sub_f32_e32 v80, v80, v8
	v_sub_f32_e32 v79, v79, v8
	v_sub_f32_e32 v78, v78, v8
	v_mov_b32_e32 v47, v46
	v_mov_b32_e32 v48, v46
	v_mov_b32_e32 v49, v46
	v_mov_b32_e32 v50, v46
	v_mov_b32_e32 v51, v46
	v_mov_b32_e32 v52, v46
	v_mov_b32_e32 v53, v46
	v_mov_b32_e32 v54, v46
	v_mov_b32_e32 v55, v46
	v_mov_b32_e32 v56, v46
	v_mov_b32_e32 v57, v46
	v_mov_b32_e32 v58, v46
	v_mov_b32_e32 v59, v46
	v_mov_b32_e32 v60, v46
	v_mov_b32_e32 v61, v46

; #define SBAR() __builtin_amdgcn_sched_barrier(0)
; #define QKT(P0, P1, KP) do { if constexpr (PRE) qkt<ND0>(P0, P1, KP, qr, r32, hi, negm); else qkt<ND0>(P0, P1, KP, qr, r32, hi); } while (0)
; #define RESC(a) do { if (__any((a) < 1.f)) { if (hi == 0) al_l[r32] = (a); asm volatile("s_waitcnt lgkmcnt(0)" ::: "memory"); \
;     _Pragma("unroll") for (int d = 0; d < NCB; ++d) _Pragma("unroll") for (int r = 0; r < 16; ++r) o[d][r] *= al_l[crow(r, hi)]; } } while (0)
; DEVFI void partialSM2(f32x16& p0, f32x16& p1, float& mhat, f32x16& negm, float& alpha, const float thr2, const bool first) {
;     ...
;     for (int r = 0; r < 16; ++r) p0[r] = __builtin_amdgcn_exp2f(p0[r]);
; }
; DEVFI void finishSM(f32x16& p0, f32x16& p1, float alpha, float& l_reg, bf16x8& pa0, bf16x8& pa1, bf16x8& pa2, bf16x8& pa3) {
; #pragma unroll
;     for (int r = 0; r < 16; ++r) p1[r] = __builtin_amdgcn_exp2f(p1[r]);
;     float ps = 0;
; #pragma unroll
;     for (int r = 0; r < 16; ++r) ps += p0[r];
; #pragma unroll
;     for (int r = 0; r < 16; ++r) ps += p1[r];
;     { auto rr = __builtin_amdgcn_permlane32_swap(__float_as_uint(ps), __float_as_uint(ps), false, false);
;       ps = __uint_as_float(rr[0]) + __uint_as_float(rr[1]); }
;     l_reg = l_reg * alpha + ps;
;     ...
;     PK4(p0, 0, pa0); PK4(p0, 8, pa1); PK4(p1, 0, pa2); PK4(p1, 8, pa3);
;     ...
; }
; template <int DQK, int DV, bool PRE = false>
; DEVFI void attn_unit(const bf16_t* __restrict__ Qb, int ldq, const bf16_t* __restrict__ Kh, int ldk, const bf16_t* __restrict__ Vh, int ldv,
;                      bf16_t* __restrict__ Ob, int ldo, int seq, float scale, char* lds) {
;     ...
;         RESC(alB); __syncthreads();
;         SBAR(); QKT(pA0, pA1, K_lds);
;         finishSM(pB0, pB1, alB, l_reg, pa0, pa1, pa2, pa3); SBAR();
;         if (j + 3 < NT) SLOAD(0, (j + 3) * KVBLK); SBAR();
.LBB0_1161:
	v_exp_f32_e32 v8, v94
	v_exp_f32_e32 v9, v96
	v_exp_f32_e32 v10, v98
	v_exp_f32_e32 v11, v100
	v_exp_f32_e32 v205, v95
	v_exp_f32_e32 v204, v97
	v_exp_f32_e32 v203, v99
	v_exp_f32_e32 v202, v101
	v_exp_f32_e32 v187, v102
	v_exp_f32_e32 v189, v103
	v_exp_f32_e32 v185, v104
	v_exp_f32_e32 v188, v105
	v_exp_f32_e32 v183, v106
	v_exp_f32_e32 v186, v107
	v_exp_f32_e32 v182, v108
	v_exp_f32_e32 v184, v109
	s_waitcnt lgkmcnt(0)
	s_barrier
	ds_read_b128 v[62:65], v177 offset:16384
	ds_read_b128 v[206:209], v177 offset:24576
	v_exp_f32_e32 v190, v78
	v_add_f32_e32 v78, v8, v205
	s_waitcnt lgkmcnt(1)
	v_mfma_f32_32x32x16_bf16 v[94:109], v[62:65], v[130:133], v[46:61]
	v_add_f32_e32 v78, v9, v78
	v_add_f32_e32 v78, v204, v78
	v_add_f32_e32 v78, v10, v78
	v_add_f32_e32 v78, v203, v78
	v_add_f32_e32 v78, v11, v78
	v_add_f32_e32 v78, v202, v78
	v_add_f32_e32 v78, v187, v78
	s_waitcnt lgkmcnt(0)
	v_mfma_f32_32x32x16_bf16 v[62:77], v[206:209], v[130:133], v[46:61]
	ds_read_b128 v[206:209], v178 offset:16384
	ds_read_b128 v[210:213], v178 offset:24576
	v_add_f32_e32 v78, v189, v78
	v_add_f32_e32 v78, v185, v78
	v_add_f32_e32 v78, v188, v78
	v_add_f32_e32 v78, v183, v78
	v_exp_f32_e32 v191, v79
	v_add_f32_e32 v78, v186, v78
	s_waitcnt lgkmcnt(1)
	v_mfma_f32_32x32x16_bf16 v[94:109], v[206:209], v[126:129], v[94:109]
	v_add_f32_e32 v78, v182, v78
	v_add_f32_e32 v78, v184, v78
	v_add_f32_e32 v78, v190, v78
	v_add_f32_e32 v78, v191, v78
	v_exp_f32_e32 v85, v85
	v_exp_f32_e32 v86, v86
	v_exp_f32_e32 v87, v87
	s_waitcnt lgkmcnt(0)
	v_mfma_f32_32x32x16_bf16 v[62:77], v[210:213], v[126:129], v[62:77]
	ds_read_b128 v[206:209], v176 offset:16384
	ds_read_b128 v[210:213], v176 offset:24576
	v_exp_f32_e32 v88, v88
	v_exp_f32_e32 v89, v89
	v_exp_f32_e32 v92, v92
	v_exp_f32_e32 v93, v93
	s_waitcnt lgkmcnt(1)
	v_mfma_f32_32x32x16_bf16 v[94:109], v[206:209], v[122:125], v[94:109]
	s_waitcnt lgkmcnt(0)
	v_mfma_f32_32x32x16_bf16 v[62:77], v[210:213], v[122:125], v[62:77]
	ds_read_b128 v[206:209], v175 offset:16384
	ds_read_b128 v[210:213], v175 offset:24576
	s_waitcnt lgkmcnt(1)
	v_mfma_f32_32x32x16_bf16 v[94:109], v[206:209], v[118:121], v[94:109]
	s_waitcnt lgkmcnt(0)
	v_mfma_f32_32x32x16_bf16 v[62:77], v[210:213], v[118:121], v[62:77]
	ds_read_b128 v[206:209], v174 offset:16384
	ds_read_b128 v[210:213], v174 offset:24576
	s_waitcnt lgkmcnt(1)
	v_mfma_f32_32x32x16_bf16 v[94:109], v[206:209], v[114:117], v[94:109]
	s_waitcnt lgkmcnt(0)
	v_mfma_f32_32x32x16_bf16 v[62:77], v[210:213], v[114:117], v[62:77]
	ds_read_b128 v[206:209], v172 offset:16384
	ds_read_b128 v[210:213], v172 offset:24576
	v_cvt_pk_bf16_f32 v8, v8, v205
	v_cvt_pk_bf16_f32 v9, v9, v204
	v_cvt_pk_bf16_f32 v10, v10, v203
	v_cvt_pk_bf16_f32 v11, v11, v202
	s_nop 0
	v_permlane32_swap_b32_e32 v8, v10
	s_waitcnt lgkmcnt(1)
	v_mfma_f32_32x32x16_bf16 v[94:109], v[206:209], v[110:113], v[94:109]
	v_exp_f32_e32 v206, v80
	v_exp_f32_e32 v207, v81
	v_exp_f32_e32 v208, v82
	v_exp_f32_e32 v209, v83
	v_add_f32_e32 v78, v206, v78
	v_add_f32_e32 v78, v207, v78
	v_add_f32_e32 v78, v208, v78
	s_waitcnt lgkmcnt(0)
	v_mfma_f32_32x32x16_bf16 v[62:77], v[210:213], v[110:113], v[62:77]
	v_exp_f32_e32 v210, v84
	v_add_f32_e32 v78, v209, v78
	v_exp_f32_e32 v211, v90
	v_exp_f32_e32 v212, v91
	v_add_f32_e32 v78, v210, v78
	v_add_f32_e32 v78, v85, v78
	v_add_f32_e32 v78, v86, v78
	v_add_f32_e32 v78, v87, v78
	v_add_f32_e32 v78, v88, v78
	v_add_f32_e32 v78, v89, v78
	v_add_f32_e32 v78, v211, v78
	v_add_f32_e32 v78, v212, v78
	v_add_f32_e32 v78, v92, v78
	v_add_f32_e32 v90, v93, v78
	v_cvt_pk_bf16_f32 v78, v187, v189
	v_cvt_pk_bf16_f32 v79, v185, v188
	v_cvt_pk_bf16_f32 v80, v183, v186
	v_cvt_pk_bf16_f32 v81, v182, v184
	v_cvt_pk_bf16_f32 v82, v190, v191
	v_cvt_pk_bf16_f32 v83, v206, v207
	v_cvt_pk_bf16_f32 v84, v208, v209
	v_cvt_pk_bf16_f32 v85, v210, v85
	v_cvt_pk_bf16_f32 v86, v86, v87
	v_cvt_pk_bf16_f32 v87, v88, v89
	v_cvt_pk_bf16_f32 v88, v211, v212
	v_cvt_pk_bf16_f32 v89, v92, v93
	s_add_u32 s100, s10, 0x2cc60000
	s_addc_u32 s101, s11, 0
	v_permlane32_swap_b32_e32 v9, v11
	v_permlane32_swap_b32_e32 v78, v80
	v_permlane32_swap_b32_e32 v79, v81
	v_permlane32_swap_b32_e32 v82, v84
	v_permlane32_swap_b32_e32 v83, v85
	v_permlane32_swap_b32_e32 v86, v88
	v_permlane32_swap_b32_e32 v87, v89
	s_cmp_ge_u32 s18, s59
	s_cselect_b64 s[0:1], -1, 0
	s_and_b64 vcc, exec, s[0:1]
	s_cbranch_vccnz .LBB0_1165
	global_load_dwordx4 v[142:145], v158, s[100:101]
	s_and_saveexec_b64 s[16:17], s[42:43]
	s_cbranch_execz .LBB0_1164
	global_load_dwordx4 v[134:137], v154, s[100:101]
; #define SBAR() __builtin_amdgcn_sched_barrier(0)
; template <int OFF> DEVFI s16x4 tr_read(int vb) { s16x4 r; asm volatile("ds_read_b64_tr_b16 %0, %1 offset:%2" : "=&v"(r) : "v"(vb), "i"(OFF) : "memory"); return r; }
; DEVFI void partialSM2(f32x16& p0, f32x16& p1, float& mhat, f32x16& negm, float& alpha, const float thr2, const bool first) {
;     float pmax = p0[0];
; #pragma unroll
;     for (int r = 1; r < 16; ++r) pmax = fmaxf(pmax, p0[r]);
; #pragma unroll
;     for (int r = 0; r < 16; ++r) pmax = fmaxf(pmax, p1[r]);
;     { auto rr = __builtin_amdgcn_permlane32_swap(__float_as_uint(pmax), __float_as_uint(pmax), false, false);
;       pmax = fmaxf(__uint_as_float(rr[0]), __uint_as_float(rr[1])); }
;     alpha = 1.f;
;     if (first || !__all(pmax <= thr2)) {
;         const float dl = first ? pmax : fmaxf(pmax, 0.f);
;         mhat += dl; alpha = first ? 1.f : __builtin_amdgcn_exp2f(-dl);
; #pragma unroll
;         for (int r = 0; r < 16; ++r) { p0[r] -= dl; p1[r] -= dl; }
; #pragma unroll
;         for (int r = 0; r < 16; ++r) negm[r] = -mhat;
;         asm volatile("" : "+v"(negm));
; template <int NCB, int D0> DEVFI void pv_one(f32x16& od, int vb, bf16x8 pa0, bf16x8 pa1, bf16x8 pa2, bf16x8 pa3) {
;     ...
;     const s16x4 l0 = tr_read<VOFF(0, 0)>(vb), h0 = tr_read<VOFF(0, 1)>(vb), l1 = tr_read<VOFF(1, 0)>(vb), h1 = tr_read<VOFF(1, 1)>(vb);
;     const s16x4 l2 = tr_read<VOFF(2, 0)>(vb), h2 = tr_read<VOFF(2, 1)>(vb), l3 = tr_read<VOFF(3, 0)>(vb), h3 = tr_read<VOFF(3, 1)>(vb);
;     ...
;     asm volatile("s_waitcnt lgkmcnt(0)" ::: "memory"); SBAR();
;     ...
;     od = __builtin_amdgcn_mfma_f32_32x32x16_bf16(pa0, PK(l0, h0), od, 0, 0, 0);
;     od = __builtin_amdgcn_mfma_f32_32x32x16_bf16(pa1, PK(l1, h1), od, 0, 0, 0);
;     od = __builtin_amdgcn_mfma_f32_32x32x16_bf16(pa2, PK(l2, h2), od, 0, 0, 0);
;     od = __builtin_amdgcn_mfma_f32_32x32x16_bf16(pa3, PK(l3, h3), od, 0, 0, 0);
.LBB0_1164:
	s_or_b64 exec, exec, s[16:17]
	s_add_u32 s100, s10, 0x2fc40000
	s_addc_u32 s101, s11, 0
	global_load_dwordx4 v[146:149], v156, s[100:101]
.LBB0_1165:
	ds_read_b64_tr_b16 v[160:161], v167 offset:0
	ds_read_b64_tr_b16 v[162:163], v167 offset:0x400
	ds_read_b64_tr_b16 v[182:183], v167 offset:0x800
	ds_read_b64_tr_b16 v[184:185], v167 offset:0xc00
	ds_read_b64_tr_b16 v[186:187], v167 offset:0x1000
	ds_read_b64_tr_b16 v[188:189], v167 offset:0x1400
	ds_read_b64_tr_b16 v[202:203], v167 offset:0x1800
	ds_read_b64_tr_b16 v[204:205], v167 offset:0x1c00
	s_waitcnt lgkmcnt(6)
	s_nop 0
	v_mfma_f32_32x32x16_bf16 v[30:45], v[8:11], v[160:163], v[30:45]
	ds_read_b64_tr_b16 v[160:161], v167 offset:0x200
	ds_read_b64_tr_b16 v[162:163], v167 offset:0x600
	s_waitcnt lgkmcnt(6)
	v_mfma_f32_32x32x16_bf16 v[30:45], v[78:81], v[182:185], v[30:45]
	ds_read_b64_tr_b16 v[182:183], v167 offset:0xa00
	ds_read_b64_tr_b16 v[184:185], v167 offset:0xe00
	s_waitcnt lgkmcnt(6)
	v_mfma_f32_32x32x16_bf16 v[30:45], v[82:85], v[186:189], v[30:45]
	ds_read_b64_tr_b16 v[186:187], v167 offset:0x1200
	ds_read_b64_tr_b16 v[188:189], v167 offset:0x1600
	s_waitcnt lgkmcnt(6)
	v_mfma_f32_32x32x16_bf16 v[30:45], v[86:89], v[202:205], v[30:45]
	ds_read_b64_tr_b16 v[202:203], v167 offset:0x1a00
	ds_read_b64_tr_b16 v[204:205], v167 offset:0x1e00
	s_waitcnt lgkmcnt(6)
	v_mfma_f32_32x32x16_bf16 v[14:29], v[8:11], v[160:163], v[14:29]
	v_max_f32_e32 v8, v94, v95
	v_max3_f32 v8, v8, v96, v97
	v_max3_f32 v8, v8, v98, v99
	v_max3_f32 v8, v8, v100, v101
	v_max3_f32 v8, v8, v102, v103
	s_waitcnt lgkmcnt(4)
	v_mfma_f32_32x32x16_bf16 v[14:29], v[78:81], v[182:185], v[14:29]
	v_max3_f32 v8, v8, v104, v105
	v_max3_f32 v8, v8, v106, v107
	v_max3_f32 v8, v8, v108, v109
	v_max3_f32 v8, v8, v62, v63
	v_max3_f32 v8, v8, v64, v65
	v_max3_f32 v8, v8, v66, v67
	v_max3_f32 v8, v8, v68, v69
	s_waitcnt lgkmcnt(2)
	v_mfma_f32_32x32x16_bf16 v[14:29], v[82:85], v[186:189], v[14:29]
	v_max3_f32 v8, v8, v70, v71
	v_max3_f32 v8, v8, v72, v73
	v_max3_f32 v8, v8, v74, v75
	v_max3_f32 v9, v8, v76, v77
	s_waitcnt lgkmcnt(0)
	v_mfma_f32_32x32x16_bf16 v[14:29], v[86:89], v[202:205], v[14:29]
	v_cmp_ge_f32_e32 vcc, s33, v9
	s_cmp_eq_u64 vcc, exec
	s_cselect_b32 s100, 0, 1
	v_mov_b32_e32 v8, 1.0
	s_cbranch_scc1 .LBB0_1167
	v_mov_b32_e32 v10, v9
	s_nop 1
	v_permlane32_swap_b32_e32 v9, v10
	v_max_f32_e32 v9, v9, v10
	v_max_f32_e32 v8, v9, v9
	v_max_f32_e32 v10, 0, v8
	v_exp_f32_e64 v8, -v10
	v_add_f32_e32 v168, v168, v10
	v_xor_b32_e32 v46, 0x80000000, v168
	v_pk_add_f32 v[94:95], v[94:95], v[10:11] op_sel_hi:[1,0] neg_lo:[0,1] neg_hi:[0,1]
	v_pk_add_f32 v[96:97], v[96:97], v[10:11] op_sel_hi:[1,0] neg_lo:[0,1] neg_hi:[0,1]
	v_pk_add_f32 v[98:99], v[98:99], v[10:11] op_sel_hi:[1,0] neg_lo:[0,1] neg_hi:[0,1]
	v_pk_add_f32 v[100:101], v[100:101], v[10:11] op_sel_hi:[1,0] neg_lo:[0,1] neg_hi:[0,1]
	v_pk_add_f32 v[102:103], v[102:103], v[10:11] op_sel_hi:[1,0] neg_lo:[0,1] neg_hi:[0,1]
	v_pk_add_f32 v[104:105], v[104:105], v[10:11] op_sel_hi:[1,0] neg_lo:[0,1] neg_hi:[0,1]
	v_pk_add_f32 v[106:107], v[106:107], v[10:11] op_sel_hi:[1,0] neg_lo:[0,1] neg_hi:[0,1]
	v_pk_add_f32 v[108:109], v[108:109], v[10:11] op_sel_hi:[1,0] neg_lo:[0,1] neg_hi:[0,1]
	v_sub_f32_e32 v77, v77, v10
	v_sub_f32_e32 v76, v76, v10
	v_sub_f32_e32 v75, v75, v10
	v_sub_f32_e32 v74, v74, v10
	v_sub_f32_e32 v73, v73, v10
	v_sub_f32_e32 v72, v72, v10
	v_sub_f32_e32 v71, v71, v10
	v_sub_f32_e32 v70, v70, v10
	v_sub_f32_e32 v69, v69, v10
	v_sub_f32_e32 v68, v68, v10
	v_sub_f32_e32 v67, v67, v10
	v_sub_f32_e32 v66, v66, v10
	v_sub_f32_e32 v65, v65, v10
	v_sub_f32_e32 v64, v64, v10
	v_sub_f32_e32 v63, v63, v10
	v_sub_f32_e32 v62, v62, v10
	v_mov_b32_e32 v47, v46
	v_mov_b32_e32 v48, v46
	v_mov_b32_e32 v49, v46
	v_mov_b32_e32 v50, v46
	v_mov_b32_e32 v51, v46
	v_mov_b32_e32 v52, v46
	v_mov_b32_e32 v53, v46
	v_mov_b32_e32 v54, v46
	v_mov_b32_e32 v55, v46
	v_mov_b32_e32 v56, v46
	v_mov_b32_e32 v57, v46
	v_mov_b32_e32 v58, v46
	v_mov_b32_e32 v59, v46
	v_mov_b32_e32 v60, v46
	v_mov_b32_e32 v61, v46
